# EpiResFinal: pass-1 rotating residual prefetch + pass-2 prefetch of row groups 1-2 (software-pipelined final epilogue)
# speedup vs baseline: 1.0016x; 1.0016x over previous
; #define LAS __attribute__((address_space(3)))
; __device__ __forceinline__ float bflo(unsigned w) { return __uint_as_float(w << 16); }
; __device__ __forceinline__ float bfhi(unsigned w) { return __uint_as_float(w & 0xffff0000u); }
;     __device__ __forceinline__ void operator()(const f32x4 (&acc)[2][2][4][2], const Unit& u, int wr, int wc, int fr, int fq, const LAS float* rsl) const {
;     ...
;         f32x4 wf[2][2];
; #pragma unroll
;         for (int bj = 0; bj < 2; ++bj) { const int col = u.pn * 256 + bj * 128 + wc * 32 + 8 * fq; wf[bj][0] = *(const f32x4*)(gfin + col); wf[bj][1] = *(const f32x4*)(gfin + col + 4); }
; #pragma unroll
;         for (int ai = 0; ai < 2; ++ai)
; #pragma unroll
;             for (int m = 0; m < 4; ++m) { const float rs = *(LAS float*)(lx + 4096 + (ai * 128 + wr * 64 + m * 16 + fr) * 4);
;                 u32x4 g2[2];
; #pragma unroll
;                 for (int bj = 0; bj < 2; ++bj) g2[bj] = *(const u32x4*)(xb + (size_t)(row0 + ai * 128 + m * 16) * 1024 + u.pn * 256 + bj * 128 + wc * 32 + 8 * fq);
; #pragma unroll
;                 for (int bj = 0; bj < 2; ++bj) { const u32x4 gg = g2[bj]; f32x4 v0 = acc[ai][bj][m][0], v1 = acc[ai][bj][m][1];
;                     v0[0] += bflo(gg.x); v0[1] += bfhi(gg.x); v0[2] += bflo(gg.y); v0[3] += bfhi(gg.y); v1[0] += bflo(gg.z); v1[1] += bfhi(gg.z); v1[2] += bflo(gg.w); v1[3] += bfhi(gg.w);
;                     float* op = out + (size_t)(row0 + ai * 128 + m * 16) * 1024 + u.pn * 256 + bj * 128 + wc * 32 + 8 * fq;
;                     *(f32x4*)op = v0 * rs * wf[bj][0]; *(f32x4*)(op + 4) = v1 * rs * wf[bj][1]; }
;                 if (m & 1) asm volatile("" ::: "memory"); }
.LBB0_171:
	s_or_b64 exec, exec, s[2:3]
	v_or_b32_e32 v130, s0, v209
	v_mov_b32_e32 v128, s16
	v_mov_b32_e32 v129, s17
	v_ashrrev_i32_e32 v131, 31, v130
	v_add_u32_e32 v219, 0, v207
	v_lshl_add_u64 v[132:133], v[130:131], 2, v[128:129]
	v_add_u32_e32 v152, 0x21800, v219
	s_waitcnt lgkmcnt(0)
	s_barrier
	global_load_dwordx4 v[136:139], v[132:133], off offset:16
	global_load_dwordx4 v[140:143], v[132:133], off
	global_load_dwordx4 v[128:131], v[132:133], off offset:528
	s_nop 0
	global_load_dwordx4 v[132:135], v[132:133], off offset:512
	ds_read_b32 v152, v152
	global_load_dwordx4 v[228:231], v[194:195], off
	global_load_dwordx4 v[232:235], v[194:195], off offset:256
	global_load_dwordx4 v[236:239], v[202:203], off
	global_load_dwordx4 v[240:243], v[202:203], off offset:256
	s_lshl_b64 s[0:1], s[0:1], 2
	s_add_u32 s0, s18, s0
	s_addc_u32 s1, s19, s1
	s_add_u32 s0, s0, s54
	s_addc_u32 s1, s1, 0
	v_lshl_add_u64 v[204:205], s[0:1], 0, v[146:147]
	v_lshlrev_b64 v[184:185], 12, v[184:185]
	v_lshl_add_u64 v[184:185], v[204:205], 0, v[184:185]
	s_mov_b64 s[0:1], -1
	s_and_b64 vcc, exec, s[12:13]
	s_waitcnt vmcnt(3)
	v_lshlrev_b32_e32 v194, 16, v228
	v_and_b32_e32 v195, 0xffff0000, v228
	v_pk_add_f32 v[124:125], v[124:125], v[194:195]
	v_lshlrev_b32_e32 v194, 16, v229
	v_and_b32_e32 v195, 0xffff0000, v229
	v_pk_add_f32 v[126:127], v[126:127], v[194:195]
	v_lshlrev_b32_e32 v194, 16, v230
	v_and_b32_e32 v195, 0xffff0000, v230
	v_pk_add_f32 v[194:195], v[120:121], v[194:195]
	v_lshlrev_b32_e32 v120, 16, v231
	v_and_b32_e32 v121, 0xffff0000, v231
	v_pk_add_f32 v[228:229], v[122:123], v[120:121]
	s_waitcnt lgkmcnt(0)
	v_pk_mul_f32 v[120:121], v[152:153], v[126:127] op_sel_hi:[0,1]
	v_pk_mul_f32 v[124:125], v[152:153], v[124:125] op_sel_hi:[0,1]
	v_pk_mul_f32 v[122:123], v[142:143], v[120:121]
	v_pk_mul_f32 v[120:121], v[140:141], v[124:125]
	global_store_dwordx4 v[184:185], v[120:123], off
	v_pk_mul_f32 v[124:125], v[152:153], v[194:195] op_sel_hi:[0,1]
	s_nop 0
	v_pk_mul_f32 v[120:121], v[152:153], v[228:229] op_sel_hi:[0,1]
	v_pk_mul_f32 v[122:123], v[138:139], v[120:121]
	v_pk_mul_f32 v[120:121], v[136:137], v[124:125]
	global_store_dwordx4 v[184:185], v[120:123], off offset:16
	s_waitcnt vmcnt(4)
	s_nop 0
	v_lshlrev_b32_e32 v120, 16, v232
	v_and_b32_e32 v121, 0xffff0000, v232
	v_pk_add_f32 v[116:117], v[116:117], v[120:121]
	v_lshlrev_b32_e32 v120, 16, v233
	v_and_b32_e32 v121, 0xffff0000, v233
	v_pk_add_f32 v[118:119], v[118:119], v[120:121]
	v_lshlrev_b32_e32 v120, 16, v234
	v_and_b32_e32 v121, 0xffff0000, v234
	v_pk_add_f32 v[120:121], v[112:113], v[120:121]
	v_lshlrev_b32_e32 v112, 16, v235
	v_and_b32_e32 v113, 0xffff0000, v235
	v_pk_add_f32 v[122:123], v[114:115], v[112:113]
	v_pk_mul_f32 v[112:113], v[152:153], v[118:119] op_sel_hi:[0,1]
	v_pk_mul_f32 v[116:117], v[152:153], v[116:117] op_sel_hi:[0,1]
	v_pk_mul_f32 v[114:115], v[134:135], v[112:113]
	v_pk_mul_f32 v[112:113], v[132:133], v[116:117]
	global_store_dwordx4 v[184:185], v[112:115], off offset:512
	v_pk_mul_f32 v[116:117], v[152:153], v[120:121] op_sel_hi:[0,1]
	v_add_u32_e32 v120, 0x21840, v219
	v_pk_mul_f32 v[112:113], v[152:153], v[122:123] op_sel_hi:[0,1]
	v_pk_mul_f32 v[114:115], v[130:131], v[112:113]
	v_pk_mul_f32 v[112:113], v[128:129], v[116:117]
	global_store_dwordx4 v[184:185], v[112:115], off offset:528
	s_waitcnt vmcnt(4)
	s_nop 1
	v_mov_b32_e32 v116, v236
	v_mov_b32_e32 v117, v237
	v_mov_b32_e32 v118, v238
	v_mov_b32_e32 v119, v239
	v_mov_b32_e32 v112, v240
	v_mov_b32_e32 v113, v241
	v_mov_b32_e32 v114, v242
	v_mov_b32_e32 v115, v243
	global_load_dwordx4 v[228:231], v[192:193], off
	global_load_dwordx4 v[232:235], v[192:193], off offset:256
	s_nop 0
	ds_read_b32 v120, v120
	v_lshlrev_b64 v[122:123], 12, v[182:183]
	v_lshl_add_u64 v[122:123], v[204:205], 0, v[122:123]
	v_lshlrev_b32_e32 v124, 16, v116
	v_and_b32_e32 v125, 0xffff0000, v116
	v_lshlrev_b32_e32 v116, 16, v117
	v_and_b32_e32 v117, 0xffff0000, v117
	v_pk_add_f32 v[110:111], v[110:111], v[116:117]
	v_lshlrev_b32_e32 v116, 16, v118
	v_and_b32_e32 v117, 0xffff0000, v118
	v_pk_add_f32 v[108:109], v[108:109], v[124:125]
	v_pk_add_f32 v[116:117], v[104:105], v[116:117]
	v_lshlrev_b32_e32 v104, 16, v119
	v_and_b32_e32 v105, 0xffff0000, v119
	v_pk_add_f32 v[118:119], v[106:107], v[104:105]
	s_waitcnt lgkmcnt(0)
	v_pk_mul_f32 v[104:105], v[120:121], v[110:111] op_sel_hi:[0,1]
	v_pk_mul_f32 v[108:109], v[120:121], v[108:109] op_sel_hi:[0,1]
	v_pk_mul_f32 v[106:107], v[142:143], v[104:105]
	v_pk_mul_f32 v[104:105], v[140:141], v[108:109]
	global_store_dwordx4 v[122:123], v[104:107], off
	v_pk_mul_f32 v[108:109], v[120:121], v[116:117] op_sel_hi:[0,1]
	s_nop 0
	v_pk_mul_f32 v[104:105], v[120:121], v[118:119] op_sel_hi:[0,1]
	v_pk_mul_f32 v[106:107], v[138:139], v[104:105]
	v_pk_mul_f32 v[104:105], v[136:137], v[108:109]
	global_store_dwordx4 v[122:123], v[104:107], off offset:16
	s_nop 1
	v_lshlrev_b32_e32 v104, 16, v112
	v_and_b32_e32 v105, 0xffff0000, v112
	v_pk_add_f32 v[100:101], v[100:101], v[104:105]
	v_lshlrev_b32_e32 v104, 16, v113
	v_and_b32_e32 v105, 0xffff0000, v113
	v_pk_add_f32 v[102:103], v[102:103], v[104:105]
	v_lshlrev_b32_e32 v104, 16, v114
	v_and_b32_e32 v105, 0xffff0000, v114
	v_pk_add_f32 v[104:105], v[96:97], v[104:105]
	v_lshlrev_b32_e32 v96, 16, v115
	v_and_b32_e32 v97, 0xffff0000, v115
	v_pk_add_f32 v[106:107], v[98:99], v[96:97]
	v_pk_mul_f32 v[96:97], v[120:121], v[102:103] op_sel_hi:[0,1]
	v_pk_mul_f32 v[100:101], v[120:121], v[100:101] op_sel_hi:[0,1]
	v_pk_mul_f32 v[98:99], v[134:135], v[96:97]
	v_pk_mul_f32 v[96:97], v[132:133], v[100:101]
	global_store_dwordx4 v[122:123], v[96:99], off offset:512
	v_pk_mul_f32 v[100:101], v[120:121], v[104:105] op_sel_hi:[0,1]
	s_nop 0
	v_pk_mul_f32 v[96:97], v[120:121], v[106:107] op_sel_hi:[0,1]
	v_pk_mul_f32 v[98:99], v[130:131], v[96:97]
	v_pk_mul_f32 v[96:97], v[128:129], v[100:101]
	global_store_dwordx4 v[122:123], v[96:99], off offset:528
	v_lshlrev_b64 v[106:107], 12, v[190:191]
	v_lshl_add_u64 v[106:107], v[204:205], 0, v[106:107]
	v_add_u32_e32 v96, 0x21880, v219
	ds_read_b32 v104, v96
	s_waitcnt vmcnt(4)
; #define LAS __attribute__((address_space(3)))
; __device__ __forceinline__ float bflo(unsigned w) { return __uint_as_float(w << 16); }
; __device__ __forceinline__ float bfhi(unsigned w) { return __uint_as_float(w & 0xffff0000u); }
;     __device__ __forceinline__ void operator()(const f32x4 (&acc)[2][2][4][2], const Unit& u, int wr, int wc, int fr, int fq, const LAS float* rsl) const {
;     ...
; #pragma unroll
;         for (int ai = 0; ai < 2; ++ai)
; #pragma unroll
;             for (int m = 0; m < 4; ++m) { const float rs = *(LAS float*)(lx + 4096 + (ai * 128 + wr * 64 + m * 16 + fr) * 4);
;                 u32x4 g2[2];
; #pragma unroll
;                 for (int bj = 0; bj < 2; ++bj) g2[bj] = *(const u32x4*)(xb + (size_t)(row0 + ai * 128 + m * 16) * 1024 + u.pn * 256 + bj * 128 + wc * 32 + 8 * fq);
; #pragma unroll
;                 for (int bj = 0; bj < 2; ++bj) { const u32x4 gg = g2[bj]; f32x4 v0 = acc[ai][bj][m][0], v1 = acc[ai][bj][m][1];
;                     v0[0] += bflo(gg.x); v0[1] += bfhi(gg.x); v0[2] += bflo(gg.y); v0[3] += bfhi(gg.y); v1[0] += bflo(gg.z); v1[1] += bfhi(gg.z); v1[2] += bflo(gg.w); v1[3] += bfhi(gg.w);
;                     float* op = out + (size_t)(row0 + ai * 128 + m * 16) * 1024 + u.pn * 256 + bj * 128 + wc * 32 + 8 * fq;
;                     *(f32x4*)op = v0 * rs * wf[bj][0]; *(f32x4*)(op + 4) = v1 * rs * wf[bj][1]; }
;                 if (m & 1) asm volatile("" ::: "memory"); }
	s_nop 1
	v_mov_b32_e32 v96, v228
	v_mov_b32_e32 v97, v229
	v_mov_b32_e32 v98, v230
	v_mov_b32_e32 v99, v231
	v_mov_b32_e32 v100, v232
	v_mov_b32_e32 v101, v233
	v_mov_b32_e32 v102, v234
	v_mov_b32_e32 v103, v235
	v_lshlrev_b32_e32 v108, 16, v96
	v_and_b32_e32 v109, 0xffff0000, v96
	v_lshlrev_b32_e32 v96, 16, v97
	v_and_b32_e32 v97, 0xffff0000, v97
	v_pk_add_f32 v[94:95], v[94:95], v[96:97]
	v_lshlrev_b32_e32 v96, 16, v98
	v_and_b32_e32 v97, 0xffff0000, v98
	v_pk_add_f32 v[92:93], v[92:93], v[108:109]
	v_pk_add_f32 v[96:97], v[88:89], v[96:97]
	v_lshlrev_b32_e32 v88, 16, v99
	v_and_b32_e32 v89, 0xffff0000, v99
	v_pk_add_f32 v[98:99], v[90:91], v[88:89]
	s_waitcnt lgkmcnt(0)
	v_pk_mul_f32 v[88:89], v[104:105], v[94:95] op_sel_hi:[0,1]
	v_pk_mul_f32 v[92:93], v[104:105], v[92:93] op_sel_hi:[0,1]
	v_pk_mul_f32 v[90:91], v[142:143], v[88:89]
	v_pk_mul_f32 v[88:89], v[140:141], v[92:93]
	global_store_dwordx4 v[106:107], v[88:91], off
	v_pk_mul_f32 v[92:93], v[104:105], v[96:97] op_sel_hi:[0,1]
	s_nop 0
	v_pk_mul_f32 v[88:89], v[104:105], v[98:99] op_sel_hi:[0,1]
	v_pk_mul_f32 v[90:91], v[138:139], v[88:89]
	v_pk_mul_f32 v[88:89], v[136:137], v[92:93]
	global_store_dwordx4 v[106:107], v[88:91], off offset:16
	s_nop 0
	v_lshlrev_b32_e32 v88, 16, v100
	v_and_b32_e32 v89, 0xffff0000, v100
	v_pk_add_f32 v[84:85], v[84:85], v[88:89]
	v_lshlrev_b32_e32 v88, 16, v101
	v_and_b32_e32 v89, 0xffff0000, v101
	v_pk_add_f32 v[86:87], v[86:87], v[88:89]
	v_lshlrev_b32_e32 v88, 16, v102
	v_and_b32_e32 v89, 0xffff0000, v102
	v_pk_add_f32 v[88:89], v[80:81], v[88:89]
	v_lshlrev_b32_e32 v80, 16, v103
	v_and_b32_e32 v81, 0xffff0000, v103
	v_pk_add_f32 v[90:91], v[82:83], v[80:81]
	v_pk_mul_f32 v[80:81], v[104:105], v[86:87] op_sel_hi:[0,1]
	v_pk_mul_f32 v[84:85], v[104:105], v[84:85] op_sel_hi:[0,1]
	v_pk_mul_f32 v[82:83], v[134:135], v[80:81]
	v_pk_mul_f32 v[80:81], v[132:133], v[84:85]
	global_store_dwordx4 v[106:107], v[80:83], off offset:512
	v_pk_mul_f32 v[84:85], v[104:105], v[88:89] op_sel_hi:[0,1]
	v_add_u32_e32 v88, 0x218c0, v219
	v_pk_mul_f32 v[80:81], v[104:105], v[90:91] op_sel_hi:[0,1]
	v_pk_mul_f32 v[82:83], v[130:131], v[80:81]
	v_pk_mul_f32 v[80:81], v[128:129], v[84:85]
	global_store_dwordx4 v[106:107], v[80:83], off offset:528
	global_load_dwordx4 v[80:83], v[200:201], off offset:256
	s_nop 0
	global_load_dwordx4 v[84:87], v[200:201], off
	ds_read_b32 v88, v88
	v_lshlrev_b64 v[90:91], 12, v[176:177]
	v_lshl_add_u64 v[90:91], v[204:205], 0, v[90:91]
	s_waitcnt vmcnt(0)
	v_lshlrev_b32_e32 v92, 16, v84
	v_and_b32_e32 v93, 0xffff0000, v84
	v_lshlrev_b32_e32 v84, 16, v85
	v_and_b32_e32 v85, 0xffff0000, v85
	v_pk_add_f32 v[78:79], v[78:79], v[84:85]
	v_lshlrev_b32_e32 v84, 16, v86
	v_and_b32_e32 v85, 0xffff0000, v86
	v_pk_add_f32 v[76:77], v[76:77], v[92:93]
	v_pk_add_f32 v[84:85], v[72:73], v[84:85]
	v_lshlrev_b32_e32 v72, 16, v87
	v_and_b32_e32 v73, 0xffff0000, v87
	v_pk_add_f32 v[86:87], v[74:75], v[72:73]
	s_waitcnt lgkmcnt(0)
	v_pk_mul_f32 v[72:73], v[88:89], v[78:79] op_sel_hi:[0,1]
	v_pk_mul_f32 v[76:77], v[88:89], v[76:77] op_sel_hi:[0,1]
	v_pk_mul_f32 v[74:75], v[142:143], v[72:73]
	v_pk_mul_f32 v[72:73], v[140:141], v[76:77]
	global_store_dwordx4 v[90:91], v[72:75], off
	v_pk_mul_f32 v[76:77], v[88:89], v[84:85] op_sel_hi:[0,1]
	s_nop 0
	v_pk_mul_f32 v[72:73], v[88:89], v[86:87] op_sel_hi:[0,1]
	v_pk_mul_f32 v[74:75], v[138:139], v[72:73]
	v_pk_mul_f32 v[72:73], v[136:137], v[76:77]
	global_store_dwordx4 v[90:91], v[72:75], off offset:16
	s_nop 1
	v_lshlrev_b32_e32 v72, 16, v80
	v_and_b32_e32 v73, 0xffff0000, v80
	v_pk_add_f32 v[68:69], v[68:69], v[72:73]
	v_lshlrev_b32_e32 v72, 16, v81
	v_and_b32_e32 v73, 0xffff0000, v81
	v_pk_add_f32 v[70:71], v[70:71], v[72:73]
	v_lshlrev_b32_e32 v72, 16, v82
	v_and_b32_e32 v73, 0xffff0000, v82
	v_pk_add_f32 v[72:73], v[64:65], v[72:73]
	v_lshlrev_b32_e32 v64, 16, v83
	v_and_b32_e32 v65, 0xffff0000, v83
	v_pk_add_f32 v[74:75], v[66:67], v[64:65]
	v_pk_mul_f32 v[64:65], v[88:89], v[70:71] op_sel_hi:[0,1]
	v_pk_mul_f32 v[68:69], v[88:89], v[68:69] op_sel_hi:[0,1]
	v_pk_mul_f32 v[66:67], v[134:135], v[64:65]
	v_pk_mul_f32 v[64:65], v[132:133], v[68:69]
	global_store_dwordx4 v[90:91], v[64:67], off offset:512
	v_pk_mul_f32 v[68:69], v[88:89], v[72:73] op_sel_hi:[0,1]
	s_nop 0
	v_pk_mul_f32 v[64:65], v[88:89], v[74:75] op_sel_hi:[0,1]
	v_pk_mul_f32 v[66:67], v[130:131], v[64:65]
	v_pk_mul_f32 v[64:65], v[128:129], v[68:69]
	global_store_dwordx4 v[90:91], v[64:67], off offset:528
	v_lshlrev_b64 v[74:75], 12, v[186:187]
	v_lshl_add_u64 v[74:75], v[204:205], 0, v[74:75]
	v_add_u32_e32 v64, 0x21a00, v219
	ds_read_b32 v72, v64
	global_load_dwordx4 v[64:67], v[188:189], off
	global_load_dwordx4 v[68:71], v[188:189], off offset:256
	s_waitcnt vmcnt(1)
	v_lshlrev_b32_e32 v76, 16, v64
	v_and_b32_e32 v77, 0xffff0000, v64
	v_lshlrev_b32_e32 v64, 16, v65
	v_and_b32_e32 v65, 0xffff0000, v65
	v_pk_add_f32 v[62:63], v[62:63], v[64:65]
	v_lshlrev_b32_e32 v64, 16, v66
	v_and_b32_e32 v65, 0xffff0000, v66
	v_pk_add_f32 v[60:61], v[60:61], v[76:77]
	v_pk_add_f32 v[64:65], v[56:57], v[64:65]
	v_lshlrev_b32_e32 v56, 16, v67
	v_and_b32_e32 v57, 0xffff0000, v67
	v_pk_add_f32 v[66:67], v[58:59], v[56:57]
	s_waitcnt lgkmcnt(0)
	v_pk_mul_f32 v[56:57], v[72:73], v[62:63] op_sel_hi:[0,1]
	v_pk_mul_f32 v[60:61], v[72:73], v[60:61] op_sel_hi:[0,1]
	v_pk_mul_f32 v[58:59], v[142:143], v[56:57]
	v_pk_mul_f32 v[56:57], v[140:141], v[60:61]
	global_store_dwordx4 v[74:75], v[56:59], off
	v_pk_mul_f32 v[60:61], v[72:73], v[64:65] op_sel_hi:[0,1]
	s_nop 0
	v_pk_mul_f32 v[56:57], v[72:73], v[66:67] op_sel_hi:[0,1]
	v_pk_mul_f32 v[58:59], v[138:139], v[56:57]
	v_pk_mul_f32 v[56:57], v[136:137], v[60:61]
	global_store_dwordx4 v[74:75], v[56:59], off offset:16
	s_waitcnt vmcnt(2)
; #define LAS __attribute__((address_space(3)))
; __device__ __forceinline__ float bflo(unsigned w) { return __uint_as_float(w << 16); }
; __device__ __forceinline__ float bfhi(unsigned w) { return __uint_as_float(w & 0xffff0000u); }
;     __device__ __forceinline__ void operator()(const f32x4 (&acc)[2][2][4][2], const Unit& u, int wr, int wc, int fr, int fq, const LAS float* rsl) const {
;     ...
; #pragma unroll
;         for (int ai = 0; ai < 2; ++ai)
; #pragma unroll
;             for (int m = 0; m < 4; ++m) { const float rs = *(LAS float*)(lx + 4096 + (ai * 128 + wr * 64 + m * 16 + fr) * 4);
;                 u32x4 g2[2];
; #pragma unroll
;                 for (int bj = 0; bj < 2; ++bj) g2[bj] = *(const u32x4*)(xb + (size_t)(row0 + ai * 128 + m * 16) * 1024 + u.pn * 256 + bj * 128 + wc * 32 + 8 * fq);
; #pragma unroll
;                 for (int bj = 0; bj < 2; ++bj) { const u32x4 gg = g2[bj]; f32x4 v0 = acc[ai][bj][m][0], v1 = acc[ai][bj][m][1];
;                     v0[0] += bflo(gg.x); v0[1] += bfhi(gg.x); v0[2] += bflo(gg.y); v0[3] += bfhi(gg.y); v1[0] += bflo(gg.z); v1[1] += bfhi(gg.z); v1[2] += bflo(gg.w); v1[3] += bfhi(gg.w);
;                     float* op = out + (size_t)(row0 + ai * 128 + m * 16) * 1024 + u.pn * 256 + bj * 128 + wc * 32 + 8 * fq;
;                     *(f32x4*)op = v0 * rs * wf[bj][0]; *(f32x4*)(op + 4) = v1 * rs * wf[bj][1]; }
;                 if (m & 1) asm volatile("" ::: "memory"); }
	s_nop 0
	v_lshlrev_b32_e32 v56, 16, v68
	v_and_b32_e32 v57, 0xffff0000, v68
	v_pk_add_f32 v[52:53], v[52:53], v[56:57]
	v_lshlrev_b32_e32 v56, 16, v69
	v_and_b32_e32 v57, 0xffff0000, v69
	v_pk_add_f32 v[54:55], v[54:55], v[56:57]
	v_lshlrev_b32_e32 v56, 16, v70
	v_and_b32_e32 v57, 0xffff0000, v70
	v_pk_add_f32 v[56:57], v[48:49], v[56:57]
	v_lshlrev_b32_e32 v48, 16, v71
	v_and_b32_e32 v49, 0xffff0000, v71
	v_pk_add_f32 v[58:59], v[50:51], v[48:49]
	v_pk_mul_f32 v[48:49], v[72:73], v[54:55] op_sel_hi:[0,1]
	v_pk_mul_f32 v[52:53], v[72:73], v[52:53] op_sel_hi:[0,1]
	v_pk_mul_f32 v[50:51], v[134:135], v[48:49]
	v_pk_mul_f32 v[48:49], v[132:133], v[52:53]
	global_store_dwordx4 v[74:75], v[48:51], off offset:512
	v_pk_mul_f32 v[52:53], v[72:73], v[56:57] op_sel_hi:[0,1]
	v_add_u32_e32 v56, 0x21a40, v219
	v_pk_mul_f32 v[48:49], v[72:73], v[58:59] op_sel_hi:[0,1]
	v_pk_mul_f32 v[50:51], v[130:131], v[48:49]
	v_pk_mul_f32 v[48:49], v[128:129], v[52:53]
	global_store_dwordx4 v[74:75], v[48:51], off offset:528
	global_load_dwordx4 v[48:51], v[198:199], off offset:256
	s_nop 0
	global_load_dwordx4 v[52:55], v[198:199], off
	ds_read_b32 v56, v56
	v_lshlrev_b64 v[58:59], 12, v[174:175]
	v_lshl_add_u64 v[58:59], v[204:205], 0, v[58:59]
	s_waitcnt vmcnt(0)
	v_lshlrev_b32_e32 v60, 16, v52
	v_and_b32_e32 v61, 0xffff0000, v52
	v_lshlrev_b32_e32 v52, 16, v53
	v_and_b32_e32 v53, 0xffff0000, v53
	v_pk_add_f32 v[46:47], v[46:47], v[52:53]
	v_lshlrev_b32_e32 v52, 16, v54
	v_and_b32_e32 v53, 0xffff0000, v54
	v_pk_add_f32 v[44:45], v[44:45], v[60:61]
	v_pk_add_f32 v[52:53], v[40:41], v[52:53]
	v_lshlrev_b32_e32 v40, 16, v55
	v_and_b32_e32 v41, 0xffff0000, v55
	v_pk_add_f32 v[54:55], v[42:43], v[40:41]
	s_waitcnt lgkmcnt(0)
	v_pk_mul_f32 v[40:41], v[56:57], v[46:47] op_sel_hi:[0,1]
	v_pk_mul_f32 v[44:45], v[56:57], v[44:45] op_sel_hi:[0,1]
	v_pk_mul_f32 v[42:43], v[142:143], v[40:41]
	v_pk_mul_f32 v[40:41], v[140:141], v[44:45]
	global_store_dwordx4 v[58:59], v[40:43], off
	v_pk_mul_f32 v[44:45], v[56:57], v[52:53] op_sel_hi:[0,1]
	s_nop 0
	v_pk_mul_f32 v[40:41], v[56:57], v[54:55] op_sel_hi:[0,1]
	v_pk_mul_f32 v[42:43], v[138:139], v[40:41]
	v_pk_mul_f32 v[40:41], v[136:137], v[44:45]
	global_store_dwordx4 v[58:59], v[40:43], off offset:16
	s_nop 1
	v_lshlrev_b32_e32 v40, 16, v48
	v_and_b32_e32 v41, 0xffff0000, v48
	v_pk_add_f32 v[36:37], v[36:37], v[40:41]
	v_lshlrev_b32_e32 v40, 16, v49
	v_and_b32_e32 v41, 0xffff0000, v49
	v_pk_add_f32 v[38:39], v[38:39], v[40:41]
	v_lshlrev_b32_e32 v40, 16, v50
	v_and_b32_e32 v41, 0xffff0000, v50
	v_pk_add_f32 v[40:41], v[32:33], v[40:41]
	v_lshlrev_b32_e32 v32, 16, v51
	v_and_b32_e32 v33, 0xffff0000, v51
	v_pk_add_f32 v[42:43], v[34:35], v[32:33]
	v_pk_mul_f32 v[32:33], v[56:57], v[38:39] op_sel_hi:[0,1]
	v_pk_mul_f32 v[36:37], v[56:57], v[36:37] op_sel_hi:[0,1]
	v_pk_mul_f32 v[34:35], v[134:135], v[32:33]
	v_pk_mul_f32 v[32:33], v[132:133], v[36:37]
	global_store_dwordx4 v[58:59], v[32:35], off offset:512
	v_pk_mul_f32 v[36:37], v[56:57], v[40:41] op_sel_hi:[0,1]
	s_nop 0
	v_pk_mul_f32 v[32:33], v[56:57], v[42:43] op_sel_hi:[0,1]
	v_pk_mul_f32 v[34:35], v[130:131], v[32:33]
	v_pk_mul_f32 v[32:33], v[128:129], v[36:37]
	global_store_dwordx4 v[58:59], v[32:35], off offset:528
	v_lshlrev_b64 v[42:43], 12, v[178:179]
	v_lshl_add_u64 v[42:43], v[204:205], 0, v[42:43]
	v_add_u32_e32 v32, 0x21a80, v219
	ds_read_b32 v40, v32
	global_load_dwordx4 v[32:35], v[180:181], off
	global_load_dwordx4 v[36:39], v[180:181], off offset:256
	s_waitcnt vmcnt(1)
	v_lshlrev_b32_e32 v44, 16, v32
	v_and_b32_e32 v45, 0xffff0000, v32
	v_lshlrev_b32_e32 v32, 16, v33
	v_and_b32_e32 v33, 0xffff0000, v33
	v_pk_add_f32 v[30:31], v[30:31], v[32:33]
	v_lshlrev_b32_e32 v32, 16, v34
	v_and_b32_e32 v33, 0xffff0000, v34
	v_pk_add_f32 v[28:29], v[28:29], v[44:45]
	v_pk_add_f32 v[32:33], v[24:25], v[32:33]
	v_lshlrev_b32_e32 v24, 16, v35
	v_and_b32_e32 v25, 0xffff0000, v35
	v_pk_add_f32 v[34:35], v[26:27], v[24:25]
	s_waitcnt lgkmcnt(0)
; #define LAS __attribute__((address_space(3)))
; __device__ __forceinline__ float bflo(unsigned w) { return __uint_as_float(w << 16); }
; __device__ __forceinline__ float bfhi(unsigned w) { return __uint_as_float(w & 0xffff0000u); }
;     __device__ __forceinline__ void operator()(const f32x4 (&acc)[2][2][4][2], const Unit& u, int wr, int wc, int fr, int fq, const LAS float* rsl) const {
;     ...
; #pragma unroll
;         for (int ai = 0; ai < 2; ++ai)
; #pragma unroll
;             for (int m = 0; m < 4; ++m) { const float rs = *(LAS float*)(lx + 4096 + (ai * 128 + wr * 64 + m * 16 + fr) * 4);
;                 u32x4 g2[2];
; #pragma unroll
;                 for (int bj = 0; bj < 2; ++bj) g2[bj] = *(const u32x4*)(xb + (size_t)(row0 + ai * 128 + m * 16) * 1024 + u.pn * 256 + bj * 128 + wc * 32 + 8 * fq);
; #pragma unroll
;                 for (int bj = 0; bj < 2; ++bj) { const u32x4 gg = g2[bj]; f32x4 v0 = acc[ai][bj][m][0], v1 = acc[ai][bj][m][1];
;                     v0[0] += bflo(gg.x); v0[1] += bfhi(gg.x); v0[2] += bflo(gg.y); v0[3] += bfhi(gg.y); v1[0] += bflo(gg.z); v1[1] += bfhi(gg.z); v1[2] += bflo(gg.w); v1[3] += bfhi(gg.w);
;                     float* op = out + (size_t)(row0 + ai * 128 + m * 16) * 1024 + u.pn * 256 + bj * 128 + wc * 32 + 8 * fq;
;                     *(f32x4*)op = v0 * rs * wf[bj][0]; *(f32x4*)(op + 4) = v1 * rs * wf[bj][1]; }
;                 if (m & 1) asm volatile("" ::: "memory"); }
	v_pk_mul_f32 v[24:25], v[40:41], v[30:31] op_sel_hi:[0,1]
	v_pk_mul_f32 v[28:29], v[40:41], v[28:29] op_sel_hi:[0,1]
	v_pk_mul_f32 v[26:27], v[142:143], v[24:25]
	v_pk_mul_f32 v[24:25], v[140:141], v[28:29]
	global_store_dwordx4 v[42:43], v[24:27], off
	v_pk_mul_f32 v[28:29], v[40:41], v[32:33] op_sel_hi:[0,1]
	s_nop 0
	v_pk_mul_f32 v[24:25], v[40:41], v[34:35] op_sel_hi:[0,1]
	v_pk_mul_f32 v[26:27], v[138:139], v[24:25]
	v_pk_mul_f32 v[24:25], v[136:137], v[28:29]
	global_store_dwordx4 v[42:43], v[24:27], off offset:16
	s_waitcnt vmcnt(2)
	s_nop 0
	v_lshlrev_b32_e32 v24, 16, v36
	v_and_b32_e32 v25, 0xffff0000, v36
	v_pk_add_f32 v[20:21], v[20:21], v[24:25]
	v_lshlrev_b32_e32 v24, 16, v37
	v_and_b32_e32 v25, 0xffff0000, v37
	v_pk_add_f32 v[22:23], v[22:23], v[24:25]
	v_lshlrev_b32_e32 v24, 16, v38
	v_and_b32_e32 v25, 0xffff0000, v38
	v_pk_add_f32 v[24:25], v[16:17], v[24:25]
	v_lshlrev_b32_e32 v16, 16, v39
	v_and_b32_e32 v17, 0xffff0000, v39
	v_pk_add_f32 v[26:27], v[18:19], v[16:17]
	v_pk_mul_f32 v[16:17], v[40:41], v[22:23] op_sel_hi:[0,1]
	v_pk_mul_f32 v[20:21], v[40:41], v[20:21] op_sel_hi:[0,1]
	v_pk_mul_f32 v[18:19], v[134:135], v[16:17]
	v_pk_mul_f32 v[16:17], v[132:133], v[20:21]
	global_store_dwordx4 v[42:43], v[16:19], off offset:512
	v_pk_mul_f32 v[20:21], v[40:41], v[24:25] op_sel_hi:[0,1]
	v_add_u32_e32 v24, 0x21ac0, v219
	v_pk_mul_f32 v[16:17], v[40:41], v[26:27] op_sel_hi:[0,1]
	v_pk_mul_f32 v[18:19], v[130:131], v[16:17]
	v_pk_mul_f32 v[16:17], v[128:129], v[20:21]
	global_store_dwordx4 v[42:43], v[16:19], off offset:528
	global_load_dwordx4 v[16:19], v[196:197], off offset:256
	s_nop 0
	global_load_dwordx4 v[20:23], v[196:197], off
	ds_read_b32 v24, v24
	v_lshlrev_b64 v[26:27], 12, v[172:173]
	v_lshl_add_u64 v[26:27], v[204:205], 0, v[26:27]
	s_waitcnt vmcnt(0)
	v_lshlrev_b32_e32 v28, 16, v20
	v_and_b32_e32 v29, 0xffff0000, v20
	v_lshlrev_b32_e32 v20, 16, v21
	v_and_b32_e32 v21, 0xffff0000, v21
	v_pk_add_f32 v[14:15], v[14:15], v[20:21]
	v_lshlrev_b32_e32 v20, 16, v22
	v_and_b32_e32 v21, 0xffff0000, v22
	v_pk_add_f32 v[12:13], v[12:13], v[28:29]
	v_pk_add_f32 v[20:21], v[8:9], v[20:21]
	v_lshlrev_b32_e32 v8, 16, v23
	v_and_b32_e32 v9, 0xffff0000, v23
	v_pk_add_f32 v[22:23], v[10:11], v[8:9]
	s_waitcnt lgkmcnt(0)
	v_pk_mul_f32 v[8:9], v[24:25], v[14:15] op_sel_hi:[0,1]
	v_pk_mul_f32 v[12:13], v[24:25], v[12:13] op_sel_hi:[0,1]
	v_pk_mul_f32 v[10:11], v[142:143], v[8:9]
	v_pk_mul_f32 v[8:9], v[140:141], v[12:13]
	global_store_dwordx4 v[26:27], v[8:11], off
	v_pk_mul_f32 v[12:13], v[24:25], v[20:21] op_sel_hi:[0,1]
	s_nop 0
	v_pk_mul_f32 v[8:9], v[24:25], v[22:23] op_sel_hi:[0,1]
	v_pk_mul_f32 v[10:11], v[138:139], v[8:9]
	v_pk_mul_f32 v[8:9], v[136:137], v[12:13]
	global_store_dwordx4 v[26:27], v[8:11], off offset:16
	s_nop 1
	v_lshlrev_b32_e32 v8, 16, v16
	v_and_b32_e32 v9, 0xffff0000, v16
	v_pk_add_f32 v[4:5], v[4:5], v[8:9]
	v_lshlrev_b32_e32 v8, 16, v17
	v_and_b32_e32 v9, 0xffff0000, v17
	v_pk_add_f32 v[6:7], v[6:7], v[8:9]
	v_lshlrev_b32_e32 v8, 16, v18
	v_and_b32_e32 v9, 0xffff0000, v18
	v_pk_add_f32 v[8:9], v[0:1], v[8:9]
	v_lshlrev_b32_e32 v0, 16, v19
	v_and_b32_e32 v1, 0xffff0000, v19
	v_pk_add_f32 v[10:11], v[2:3], v[0:1]
	v_pk_mul_f32 v[0:1], v[24:25], v[6:7] op_sel_hi:[0,1]
	v_pk_mul_f32 v[4:5], v[24:25], v[4:5] op_sel_hi:[0,1]
	v_pk_mul_f32 v[2:3], v[134:135], v[0:1]
	v_pk_mul_f32 v[0:1], v[132:133], v[4:5]
	global_store_dwordx4 v[26:27], v[0:3], off offset:512
	v_pk_mul_f32 v[4:5], v[24:25], v[8:9] op_sel_hi:[0,1]
	s_nop 0
	v_pk_mul_f32 v[0:1], v[24:25], v[10:11] op_sel_hi:[0,1]
	v_pk_mul_f32 v[2:3], v[130:131], v[0:1]
	v_pk_mul_f32 v[0:1], v[128:129], v[4:5]
	global_store_dwordx4 v[26:27], v[0:3], off offset:528
	s_cbranch_vccnz .LBB0_120
	s_andn2_b64 vcc, exec, s[26:27]
	s_cbranch_vccnz .LBB0_119
	s_barrier
	s_branch .LBB0_119
